# dec_w1 weight rows: 4 element loads per iteration issued together (was 32 serial round trips per item)
# speedup vs baseline: 1.0393x; 1.0029x over previous
.LBB0_130:
	v_ashrrev_i32_e32 v0, 10, v45
	v_add_u32_e32 v28, s8, v0
	v_cmp_gt_i32_e32 vcc, 32, v28
	v_mov_b32_e32 v220, 0
	v_mov_b32_e32 v221, 0
	v_mov_b32_e32 v222, 0
	v_mov_b32_e32 v223, 0
	s_and_saveexec_b64 s[56:57], vcc
	s_cbranch_execz .Ldw_skip_a
	v_ashrrev_i32_e32 v48, 4, v28
	v_ashrrev_i32_e32 v49, 31, v48
	v_and_b32_e32 v0, 15, v28
	v_lshlrev_b64 v[48:49], 16, v[48:49]
	v_lshlrev_b32_e32 v0, 2, v0
	v_lshl_add_u64 v[48:49], v[48:49], 0, v[0:1]
	v_lshl_add_u64 v[224:225], v[12:13], 0, v[48:49]
	global_load_dword v220, v[224:225], off
	v_lshl_add_u64 v[224:225], v[16:17], 0, v[48:49]
	global_load_dword v221, v[224:225], off
	v_lshl_add_u64 v[224:225], v[20:21], 0, v[48:49]
	global_load_dword v222, v[224:225], off
	v_lshl_add_u64 v[224:225], v[24:25], 0, v[48:49]
	global_load_dword v223, v[224:225], off
	s_waitcnt vmcnt(0)
.Ldw_skip_a:
	s_or_b64 exec, exec, s[56:57]
	v_cvt_pk_bf16_f32 v220, v220, v220
	v_cvt_pk_bf16_f32 v221, v221, v221
	v_cvt_pk_bf16_f32 v222, v222, v222
	v_cvt_pk_bf16_f32 v223, v223, v223
	v_ashrrev_i32_e32 v29, 31, v28
	v_lshlrev_b64 v[28:29], 11, v[28:29]
	v_mov_b32_e32 v226, 0x600000
	v_mov_b32_e32 v227, 0
	v_lshl_add_u64 v[28:29], v[28:29], 0, v[226:227]
	v_lshl_add_u64 v[48:49], v[14:15], 0, v[28:29]
	v_subrev_u32_e32 v240, s94, v48
	v_bfe_u32 v241, v240, 6, 5
	v_and_b32_e32 v242, 63, v240
	v_lshl_or_b32 v242, v241, 10, v242
	v_bfe_u32 v241, v240, 11, 4
	v_lshl_or_b32 v242, v241, 6, v242
	v_and_b32_e32 v241, 0x7fff, v240
	v_sub_u32_e32 v242, v242, v241
	v_ashrrev_i32_e32 v243, 31, v242
	v_lshl_add_u64 v[240:241], v[48:49], 0, v[242:243]
	global_store_short v[240:241], v220, off
	v_lshl_add_u64 v[48:49], v[18:19], 0, v[28:29]
	v_subrev_u32_e32 v240, s94, v48
	v_bfe_u32 v241, v240, 6, 5
	v_and_b32_e32 v242, 63, v240
	v_lshl_or_b32 v242, v241, 10, v242
	v_bfe_u32 v241, v240, 11, 4
	v_lshl_or_b32 v242, v241, 6, v242
	v_and_b32_e32 v241, 0x7fff, v240
	v_sub_u32_e32 v242, v242, v241
	v_ashrrev_i32_e32 v243, 31, v242
	v_lshl_add_u64 v[240:241], v[48:49], 0, v[242:243]
	global_store_short v[240:241], v221, off
	v_lshl_add_u64 v[48:49], v[22:23], 0, v[28:29]
	v_subrev_u32_e32 v240, s94, v48
	v_bfe_u32 v241, v240, 6, 5
	v_and_b32_e32 v242, 63, v240
	v_lshl_or_b32 v242, v241, 10, v242
	v_bfe_u32 v241, v240, 11, 4
	v_lshl_or_b32 v242, v241, 6, v242
	v_and_b32_e32 v241, 0x7fff, v240
	v_sub_u32_e32 v242, v242, v241
	v_ashrrev_i32_e32 v243, 31, v242
	v_lshl_add_u64 v[240:241], v[48:49], 0, v[242:243]
	global_store_short v[240:241], v222, off
	v_lshl_add_u64 v[48:49], v[26:27], 0, v[28:29]
	v_subrev_u32_e32 v240, s94, v48
	v_bfe_u32 v241, v240, 6, 5
	v_and_b32_e32 v242, 63, v240
	v_lshl_or_b32 v242, v241, 10, v242
	v_bfe_u32 v241, v240, 11, 4
	v_lshl_or_b32 v242, v241, 6, v242
	v_and_b32_e32 v241, 0x7fff, v240
	v_sub_u32_e32 v242, v242, v241
	v_ashrrev_i32_e32 v243, 31, v242
	v_lshl_add_u64 v[240:241], v[48:49], 0, v[242:243]
	global_store_short v[240:241], v223, off
	v_cmp_lt_i32_e32 vcc, s82, v45
	s_or_b64 s[54:55], vcc, s[54:55]
	v_add_u32_e32 v45, 0x400, v45
	s_andn2_b64 exec, exec, s[54:55]
	s_cbranch_execnz .LBB0_130

.LBB0_308:
	v_ashrrev_i32_e32 v0, 10, v20
	v_add_u32_e32 v18, s6, v0
	v_cmp_gt_i32_e32 vcc, 32, v18
	v_mov_b32_e32 v225, 0
	v_mov_b32_e32 v226, 0
	v_mov_b32_e32 v227, 0
	v_mov_b32_e32 v228, 0
	s_and_saveexec_b64 s[52:53], vcc
	s_cbranch_execz .Ldw_skip_b
	v_ashrrev_i32_e32 v234, 4, v18
	v_ashrrev_i32_e32 v235, 31, v234
	v_and_b32_e32 v0, 15, v18
	v_lshlrev_b64 v[234:235], 16, v[234:235]
	v_lshlrev_b32_e32 v0, 2, v0
	v_lshl_add_u64 v[234:235], v[234:235], 0, v[0:1]
	v_lshl_add_u64 v[230:231], v[2:3], 0, v[234:235]
	global_load_dword v225, v[230:231], off
	v_lshl_add_u64 v[230:231], v[6:7], 0, v[234:235]
	global_load_dword v226, v[230:231], off
	v_lshl_add_u64 v[230:231], v[10:11], 0, v[234:235]
	global_load_dword v227, v[230:231], off
	v_lshl_add_u64 v[230:231], v[14:15], 0, v[234:235]
	global_load_dword v228, v[230:231], off
	s_waitcnt vmcnt(0)
.Ldw_skip_b:
	s_or_b64 exec, exec, s[52:53]
	v_cvt_pk_bf16_f32 v225, v225, v225
	v_cvt_pk_bf16_f32 v226, v226, v226
	v_cvt_pk_bf16_f32 v227, v227, v227
	v_cvt_pk_bf16_f32 v228, v228, v228
	v_ashrrev_i32_e32 v19, 31, v18
	v_lshlrev_b64 v[18:19], 11, v[18:19]
	v_mov_b32_e32 v232, 0x600000
	v_mov_b32_e32 v233, 0
	v_lshl_add_u64 v[18:19], v[18:19], 0, v[232:233]
	v_lshl_add_u64 v[234:235], v[4:5], 0, v[18:19]
	v_subrev_u32_e32 v240, s94, v234
	v_bfe_u32 v241, v240, 6, 5
	v_and_b32_e32 v242, 63, v240
	v_lshl_or_b32 v242, v241, 10, v242
	v_bfe_u32 v241, v240, 11, 4
	v_lshl_or_b32 v242, v241, 6, v242
	v_and_b32_e32 v241, 0x7fff, v240
	v_sub_u32_e32 v242, v242, v241
	v_ashrrev_i32_e32 v243, 31, v242
	v_lshl_add_u64 v[240:241], v[234:235], 0, v[242:243]
	global_store_short v[240:241], v225, off
	v_lshl_add_u64 v[234:235], v[8:9], 0, v[18:19]
	v_subrev_u32_e32 v240, s94, v234
	v_bfe_u32 v241, v240, 6, 5
	v_and_b32_e32 v242, 63, v240
	v_lshl_or_b32 v242, v241, 10, v242
	v_bfe_u32 v241, v240, 11, 4
	v_lshl_or_b32 v242, v241, 6, v242
	v_and_b32_e32 v241, 0x7fff, v240
	v_sub_u32_e32 v242, v242, v241
	v_ashrrev_i32_e32 v243, 31, v242
	v_lshl_add_u64 v[240:241], v[234:235], 0, v[242:243]
	global_store_short v[240:241], v226, off
	v_lshl_add_u64 v[234:235], v[12:13], 0, v[18:19]
	v_subrev_u32_e32 v240, s94, v234
	v_bfe_u32 v241, v240, 6, 5
	v_and_b32_e32 v242, 63, v240
	v_lshl_or_b32 v242, v241, 10, v242
	v_bfe_u32 v241, v240, 11, 4
	v_lshl_or_b32 v242, v241, 6, v242
	v_and_b32_e32 v241, 0x7fff, v240
	v_sub_u32_e32 v242, v242, v241
	v_ashrrev_i32_e32 v243, 31, v242
	v_lshl_add_u64 v[240:241], v[234:235], 0, v[242:243]
	global_store_short v[240:241], v227, off
	v_lshl_add_u64 v[234:235], v[16:17], 0, v[18:19]
	v_subrev_u32_e32 v240, s94, v234
	v_bfe_u32 v241, v240, 6, 5
	v_and_b32_e32 v242, 63, v240
	v_lshl_or_b32 v242, v241, 10, v242
	v_bfe_u32 v241, v240, 11, 4
	v_lshl_or_b32 v242, v241, 6, v242
	v_and_b32_e32 v241, 0x7fff, v240
	v_sub_u32_e32 v242, v242, v241
	v_ashrrev_i32_e32 v243, 31, v242
	v_lshl_add_u64 v[240:241], v[234:235], 0, v[242:243]
	global_store_short v[240:241], v228, off
	v_cmp_lt_i32_e32 vcc, s82, v20
	s_or_b64 s[50:51], vcc, s[50:51]
	v_add_u32_e32 v20, 0x400, v20
	s_andn2_b64 exec, exec, s[50:51]
	s_cbranch_execnz .LBB0_308
